# thin kv tile: per-stage LDS fragment reads all issued up front into separate registers, counted lgkmcnt before each MFMA pair
# baseline (speedup 1.0000x reference)
; #define GLDS16(gp, lp) __builtin_amdgcn_global_load_lds((const unsigned*)(gp), (__attribute__((address_space(3))) unsigned*)(lp), 16, 0, 0)
; template <bool SWAP, class Epi, bool THIN = false> ...
;     ...
;     for (int st = 0; st < ns; ++st) {
;       asm volatile("s_waitcnt vmcnt(0)" ::: "memory");
;       __builtin_amdgcn_s_barrier();
;       asm volatile("" ::: "memory");
;       if (st + 1 < ns) {
;         char* nb = smem + ((st + 1) & 1) * 65536;
;         const int ko = (st + 1) * 64;
; #pragma unroll
;         for (int i = 0; i < 4; ++i) { GLDS16(A + (size_t)(ap[i] + ko), nb + tid * 16 + i * 8192); GLDS16(Bt + (size_t)(bp[i] + ko), nb + 32768 + tid * 16 + i * 8192); }
;       }
;       const char* sa = smem + (st & 1) * 65536 + (wr * 64 + fr) * 128;
;       const char* sb = smem + (st & 1) * 65536 + 32768 + (wc * 128 + fr) * 128;
;       if constexpr (THIN) {
;         if (wc == 0) {
; #pragma unroll
;           for (int ks = 0; ks < 2; ++ks) {
;             bf16x8 af[4], bf[2];
; #pragma unroll
;             for (int m = 0; m < 4; ++m) af[m] = *(const bf16x8*)(sa + m * 2048 + (((ks * 4 + fq) ^ swz) << 4));
; #pragma unroll
;             for (int n = 0; n < 2; ++n) bf[n] = *(const bf16x8*)(sb + n * 2048 + (((ks * 4 + fq) ^ swz) << 4));
; #pragma unroll
;             for (int m = 0; m < 4; ++m)
; #pragma unroll
;               for (int n = 0; n < 2; ++n)
;                 acc[m][n] = SWAP ? __builtin_amdgcn_mfma_f32_16x16x32_bf16(bf[n], af[m], acc[m][n], 0, 0, 0)
;                                  : __builtin_amdgcn_mfma_f32_16x16x32_bf16(af[m], bf[n], acc[m][n], 0, 0, 0);
;           }
;         }
.LBB0_1527:
	s_or_b64 exec, exec, s[6:7]
	s_waitcnt vmcnt(5)
	s_barrier
	v_readfirstlane_b32 s6, v56
	s_add_i32 m0, s6, 0x0
	v_lshl_add_u64 v[4:5], v[46:47], 0, s[26:27]
	global_load_lds_dwordx4 v[4:5], off
	v_or_b32_e32 v2, 0xc0, v38
	s_add_i32 m0, s6, 0x8000
	v_lshl_add_u64 v[4:5], v[2:3], 1, s[18:19]
	global_load_lds_dwordx4 v[4:5], off
	s_add_i32 m0, s6, 0x2000
	v_lshl_add_u64 v[4:5], v[48:49], 0, s[26:27]
	global_load_lds_dwordx4 v[4:5], off
	s_add_i32 m0, s6, 0x4000
	v_lshl_add_u64 v[4:5], v[50:51], 0, s[26:27]
	global_load_lds_dwordx4 v[4:5], off
	s_add_i32 m0, s6, 0x6000
	v_lshl_add_u64 v[4:5], v[52:53], 0, s[26:27]
	global_load_lds_dwordx4 v[4:5], off
	s_and_saveexec_b64 s[6:7], s[4:5]
	s_cbranch_execz .LBB0_1529
	ds_read_b128 v[94:97], v87
	ds_read_b128 v[98:101], v87 offset:2048
	ds_read_b128 v[102:105], v86
	ds_read_b128 v[106:109], v86 offset:2048
	ds_read_b128 v[122:125], v86 offset:4096
	ds_read_b128 v[126:129], v86 offset:6144
	ds_read_b128 v[130:133], v89
	ds_read_b128 v[134:137], v89 offset:2048
	ds_read_b128 v[138:141], v88
	ds_read_b128 v[142:145], v88 offset:2048
	ds_read_b128 v[146:149], v88 offset:4096
	ds_read_b128 v[150:153], v88 offset:6144
	s_waitcnt lgkmcnt(9)
	v_mfma_f32_16x16x32_bf16 v[34:37], v[94:97], v[102:105], v[34:37]
	v_mfma_f32_16x16x32_bf16 v[30:33], v[98:101], v[102:105], v[30:33]
	s_waitcnt lgkmcnt(8)
	v_mfma_f32_16x16x32_bf16 v[26:29], v[94:97], v[106:109], v[26:29]
	v_mfma_f32_16x16x32_bf16 v[22:25], v[98:101], v[106:109], v[22:25]
	s_waitcnt lgkmcnt(7)
	v_mfma_f32_16x16x32_bf16 v[18:21], v[94:97], v[122:125], v[18:21]
	v_mfma_f32_16x16x32_bf16 v[14:17], v[98:101], v[122:125], v[14:17]
	s_waitcnt lgkmcnt(6)
	v_mfma_f32_16x16x32_bf16 v[10:13], v[94:97], v[126:129], v[10:13]
	v_mfma_f32_16x16x32_bf16 v[6:9], v[98:101], v[126:129], v[6:9]
	s_waitcnt lgkmcnt(3)
	v_mfma_f32_16x16x32_bf16 v[34:37], v[130:133], v[138:141], v[34:37]
	v_mfma_f32_16x16x32_bf16 v[30:33], v[134:137], v[138:141], v[30:33]
	s_waitcnt lgkmcnt(2)
	v_mfma_f32_16x16x32_bf16 v[26:29], v[130:133], v[142:145], v[26:29]
	v_mfma_f32_16x16x32_bf16 v[22:25], v[134:137], v[142:145], v[22:25]
	s_waitcnt lgkmcnt(1)
	v_mfma_f32_16x16x32_bf16 v[18:21], v[130:133], v[146:149], v[18:21]
	v_mfma_f32_16x16x32_bf16 v[14:17], v[134:137], v[146:149], v[14:17]
	s_waitcnt lgkmcnt(0)
	v_mfma_f32_16x16x32_bf16 v[10:13], v[130:133], v[150:153], v[10:13]
	v_mfma_f32_16x16x32_bf16 v[6:9], v[134:137], v[150:153], v[6:9]
.LBB0_1529:
	s_or_b64 exec, exec, s[6:7]
	s_waitcnt vmcnt(5)
	s_barrier
	v_readfirstlane_b32 s6, v56
	s_add_i32 m0, s6, 0x10000
	v_lshl_add_u64 v[4:5], v[46:47], 0, s[28:29]
	global_load_lds_dwordx4 v[4:5], off
	v_or_b32_e32 v2, 0x100, v38
	s_add_i32 m0, s6, 0x18000
	v_lshl_add_u64 v[4:5], v[2:3], 1, s[18:19]
	global_load_lds_dwordx4 v[4:5], off
	s_add_i32 m0, s6, 0x12000
	v_lshl_add_u64 v[4:5], v[48:49], 0, s[28:29]
	global_load_lds_dwordx4 v[4:5], off
	s_add_i32 m0, s6, 0x14000
	v_lshl_add_u64 v[4:5], v[50:51], 0, s[28:29]
	global_load_lds_dwordx4 v[4:5], off
	s_add_i32 m0, s6, 0x16000
	v_lshl_add_u64 v[4:5], v[52:53], 0, s[28:29]
	global_load_lds_dwordx4 v[4:5], off
	s_and_saveexec_b64 s[6:7], s[4:5]
	s_cbranch_execz .LBB0_1531
	ds_read_b128 v[94:97], v119 offset:32768
	ds_read_b128 v[98:101], v119 offset:34816
	ds_read_b128 v[102:105], v118
	ds_read_b128 v[106:109], v118 offset:2048
	ds_read_b128 v[122:125], v118 offset:4096
	ds_read_b128 v[126:129], v118 offset:6144
	ds_read_b128 v[130:133], v121 offset:32768
	ds_read_b128 v[134:137], v121 offset:34816
	ds_read_b128 v[138:141], v120
	ds_read_b128 v[142:145], v120 offset:2048
	ds_read_b128 v[146:149], v120 offset:4096
	ds_read_b128 v[150:153], v120 offset:6144
	s_waitcnt lgkmcnt(9)
	v_mfma_f32_16x16x32_bf16 v[34:37], v[94:97], v[102:105], v[34:37]
	v_mfma_f32_16x16x32_bf16 v[30:33], v[98:101], v[102:105], v[30:33]
	s_waitcnt lgkmcnt(8)
	v_mfma_f32_16x16x32_bf16 v[26:29], v[94:97], v[106:109], v[26:29]
	v_mfma_f32_16x16x32_bf16 v[22:25], v[98:101], v[106:109], v[22:25]
	s_waitcnt lgkmcnt(7)
	v_mfma_f32_16x16x32_bf16 v[18:21], v[94:97], v[122:125], v[18:21]
	v_mfma_f32_16x16x32_bf16 v[14:17], v[98:101], v[122:125], v[14:17]
	s_waitcnt lgkmcnt(6)
	v_mfma_f32_16x16x32_bf16 v[10:13], v[94:97], v[126:129], v[10:13]
	v_mfma_f32_16x16x32_bf16 v[6:9], v[98:101], v[126:129], v[6:9]
	s_waitcnt lgkmcnt(3)
	v_mfma_f32_16x16x32_bf16 v[34:37], v[130:133], v[138:141], v[34:37]
	v_mfma_f32_16x16x32_bf16 v[30:33], v[134:137], v[138:141], v[30:33]
	s_waitcnt lgkmcnt(2)
	v_mfma_f32_16x16x32_bf16 v[26:29], v[130:133], v[142:145], v[26:29]
	v_mfma_f32_16x16x32_bf16 v[22:25], v[134:137], v[142:145], v[22:25]
	s_waitcnt lgkmcnt(1)
	v_mfma_f32_16x16x32_bf16 v[18:21], v[130:133], v[146:149], v[18:21]
	v_mfma_f32_16x16x32_bf16 v[14:17], v[134:137], v[146:149], v[14:17]
	s_waitcnt lgkmcnt(0)
	v_mfma_f32_16x16x32_bf16 v[10:13], v[130:133], v[150:153], v[10:13]
	v_mfma_f32_16x16x32_bf16 v[6:9], v[134:137], v[150:153], v[6:9]
; #define GLDS16(gp, lp) __builtin_amdgcn_global_load_lds((const unsigned*)(gp), (__attribute__((address_space(3))) unsigned*)(lp), 16, 0, 0)
; template <bool SWAP, class Epi, bool THIN = false> ...
;     ...
;     for (int st = 0; st < ns; ++st) {
;       asm volatile("s_waitcnt vmcnt(0)" ::: "memory");
;       __builtin_amdgcn_s_barrier();
;       asm volatile("" ::: "memory");
;       if (st + 1 < ns) {
;         char* nb = smem + ((st + 1) & 1) * 65536;
;         const int ko = (st + 1) * 64;
; #pragma unroll
;         for (int i = 0; i < 4; ++i) { GLDS16(A + (size_t)(ap[i] + ko), nb + tid * 16 + i * 8192); GLDS16(Bt + (size_t)(bp[i] + ko), nb + 32768 + tid * 16 + i * 8192); }
;       }
;       const char* sa = smem + (st & 1) * 65536 + (wr * 64 + fr) * 128;
;       const char* sb = smem + (st & 1) * 65536 + 32768 + (wc * 128 + fr) * 128;
;       if constexpr (THIN) {
;         if (wc == 0) {
; #pragma unroll
;           for (int ks = 0; ks < 2; ++ks) {
;             bf16x8 af[4], bf[2];
; #pragma unroll
;             for (int m = 0; m < 4; ++m) af[m] = *(const bf16x8*)(sa + m * 2048 + (((ks * 4 + fq) ^ swz) << 4));
; #pragma unroll
;             for (int n = 0; n < 2; ++n) bf[n] = *(const bf16x8*)(sb + n * 2048 + (((ks * 4 + fq) ^ swz) << 4));
; #pragma unroll
;             for (int m = 0; m < 4; ++m)
; #pragma unroll
;               for (int n = 0; n < 2; ++n)
;                 acc[m][n] = SWAP ? __builtin_amdgcn_mfma_f32_16x16x32_bf16(bf[n], af[m], acc[m][n], 0, 0, 0)
;                                  : __builtin_amdgcn_mfma_f32_16x16x32_bf16(af[m], bf[n], acc[m][n], 0, 0, 0);
;           }
;         }
.LBB0_1531:
	s_or_b64 exec, exec, s[6:7]
	s_waitcnt vmcnt(5)
	s_barrier
	v_readfirstlane_b32 s6, v56
	s_add_i32 m0, s6, 0x1a000
	v_lshl_add_u64 v[4:5], v[46:47], 0, s[38:39]
	global_load_lds_dwordx4 v[4:5], off
	v_or_b32_e32 v2, 0x140, v38
	s_add_i32 m0, s6, 0x22000
	v_lshl_add_u64 v[4:5], v[2:3], 1, s[18:19]
	global_load_lds_dwordx4 v[4:5], off
	s_add_i32 m0, s6, 0x1c000
	v_lshl_add_u64 v[4:5], v[48:49], 0, s[38:39]
	global_load_lds_dwordx4 v[4:5], off
	s_add_i32 m0, s6, 0x1e000
	v_lshl_add_u64 v[4:5], v[50:51], 0, s[38:39]
	global_load_lds_dwordx4 v[4:5], off
	s_add_i32 m0, s6, 0x20000
	v_lshl_add_u64 v[4:5], v[52:53], 0, s[38:39]
	global_load_lds_dwordx4 v[4:5], off
	s_and_saveexec_b64 s[6:7], s[4:5]
	s_cbranch_execz .LBB0_1533
	ds_read_b128 v[94:97], v83 offset:32768
	ds_read_b128 v[98:101], v83 offset:34816
	ds_read_b128 v[102:105], v82
	ds_read_b128 v[106:109], v82 offset:2048
	ds_read_b128 v[122:125], v82 offset:4096
	ds_read_b128 v[126:129], v82 offset:6144
	ds_read_b128 v[130:133], v85 offset:32768
	ds_read_b128 v[134:137], v85 offset:34816
	ds_read_b128 v[138:141], v84
	ds_read_b128 v[142:145], v84 offset:2048
	ds_read_b128 v[146:149], v84 offset:4096
	ds_read_b128 v[150:153], v84 offset:6144
	s_waitcnt lgkmcnt(9)
	v_mfma_f32_16x16x32_bf16 v[34:37], v[94:97], v[102:105], v[34:37]
	v_mfma_f32_16x16x32_bf16 v[30:33], v[98:101], v[102:105], v[30:33]
	s_waitcnt lgkmcnt(8)
	v_mfma_f32_16x16x32_bf16 v[26:29], v[94:97], v[106:109], v[26:29]
	v_mfma_f32_16x16x32_bf16 v[22:25], v[98:101], v[106:109], v[22:25]
	s_waitcnt lgkmcnt(7)
	v_mfma_f32_16x16x32_bf16 v[18:21], v[94:97], v[122:125], v[18:21]
	v_mfma_f32_16x16x32_bf16 v[14:17], v[98:101], v[122:125], v[14:17]
	s_waitcnt lgkmcnt(6)
	v_mfma_f32_16x16x32_bf16 v[10:13], v[94:97], v[126:129], v[10:13]
	v_mfma_f32_16x16x32_bf16 v[6:9], v[98:101], v[126:129], v[6:9]
	s_waitcnt lgkmcnt(3)
	v_mfma_f32_16x16x32_bf16 v[34:37], v[130:133], v[138:141], v[34:37]
	v_mfma_f32_16x16x32_bf16 v[30:33], v[134:137], v[138:141], v[30:33]
	s_waitcnt lgkmcnt(2)
	v_mfma_f32_16x16x32_bf16 v[26:29], v[130:133], v[142:145], v[26:29]
	v_mfma_f32_16x16x32_bf16 v[22:25], v[134:137], v[142:145], v[22:25]
	s_waitcnt lgkmcnt(1)
	v_mfma_f32_16x16x32_bf16 v[18:21], v[130:133], v[146:149], v[18:21]
	v_mfma_f32_16x16x32_bf16 v[14:17], v[134:137], v[146:149], v[14:17]
	s_waitcnt lgkmcnt(0)
	v_mfma_f32_16x16x32_bf16 v[10:13], v[130:133], v[150:153], v[10:13]
	v_mfma_f32_16x16x32_bf16 v[6:9], v[134:137], v[150:153], v[6:9]
.LBB0_1533:
	s_or_b64 exec, exec, s[6:7]
	s_waitcnt vmcnt(5)
	s_barrier
	v_readfirstlane_b32 s6, v56
	s_add_i32 m0, s6, 0x0
	v_lshl_add_u64 v[4:5], v[46:47], 0, s[40:41]
	global_load_lds_dwordx4 v[4:5], off
	v_or_b32_e32 v2, 0x180, v38
	s_add_i32 m0, s6, 0x8000
	v_lshl_add_u64 v[4:5], v[2:3], 1, s[18:19]
	global_load_lds_dwordx4 v[4:5], off
	s_add_i32 m0, s6, 0x2000
	v_lshl_add_u64 v[4:5], v[48:49], 0, s[40:41]
	global_load_lds_dwordx4 v[4:5], off
	s_add_i32 m0, s6, 0x4000
	v_lshl_add_u64 v[4:5], v[50:51], 0, s[40:41]
	global_load_lds_dwordx4 v[4:5], off
	s_add_i32 m0, s6, 0x6000
	v_lshl_add_u64 v[4:5], v[52:53], 0, s[40:41]
	global_load_lds_dwordx4 v[4:5], off
	s_and_saveexec_b64 s[6:7], s[4:5]
	s_cbranch_execz .LBB0_1535
	ds_read_b128 v[94:97], v87
	ds_read_b128 v[98:101], v87 offset:2048
	ds_read_b128 v[102:105], v86
	ds_read_b128 v[106:109], v86 offset:2048
	ds_read_b128 v[122:125], v86 offset:4096
	ds_read_b128 v[126:129], v86 offset:6144
	ds_read_b128 v[130:133], v89
	ds_read_b128 v[134:137], v89 offset:2048
	ds_read_b128 v[138:141], v88
	ds_read_b128 v[142:145], v88 offset:2048
	ds_read_b128 v[146:149], v88 offset:4096
	ds_read_b128 v[150:153], v88 offset:6144
	s_waitcnt lgkmcnt(9)
	v_mfma_f32_16x16x32_bf16 v[34:37], v[94:97], v[102:105], v[34:37]
	v_mfma_f32_16x16x32_bf16 v[30:33], v[98:101], v[102:105], v[30:33]
	s_waitcnt lgkmcnt(8)
	v_mfma_f32_16x16x32_bf16 v[26:29], v[94:97], v[106:109], v[26:29]
	v_mfma_f32_16x16x32_bf16 v[22:25], v[98:101], v[106:109], v[22:25]
	s_waitcnt lgkmcnt(7)
	v_mfma_f32_16x16x32_bf16 v[18:21], v[94:97], v[122:125], v[18:21]
	v_mfma_f32_16x16x32_bf16 v[14:17], v[98:101], v[122:125], v[14:17]
	s_waitcnt lgkmcnt(6)
	v_mfma_f32_16x16x32_bf16 v[10:13], v[94:97], v[126:129], v[10:13]
	v_mfma_f32_16x16x32_bf16 v[6:9], v[98:101], v[126:129], v[6:9]
	s_waitcnt lgkmcnt(3)
	v_mfma_f32_16x16x32_bf16 v[34:37], v[130:133], v[138:141], v[34:37]
	v_mfma_f32_16x16x32_bf16 v[30:33], v[134:137], v[138:141], v[30:33]
	s_waitcnt lgkmcnt(2)
	v_mfma_f32_16x16x32_bf16 v[26:29], v[130:133], v[142:145], v[26:29]
	v_mfma_f32_16x16x32_bf16 v[22:25], v[134:137], v[142:145], v[22:25]
	s_waitcnt lgkmcnt(1)
	v_mfma_f32_16x16x32_bf16 v[18:21], v[130:133], v[146:149], v[18:21]
	v_mfma_f32_16x16x32_bf16 v[14:17], v[134:137], v[146:149], v[14:17]
	s_waitcnt lgkmcnt(0)
	v_mfma_f32_16x16x32_bf16 v[10:13], v[130:133], v[150:153], v[10:13]
	v_mfma_f32_16x16x32_bf16 v[6:9], v[134:137], v[150:153], v[6:9]
; #define GLDS16(gp, lp) __builtin_amdgcn_global_load_lds((const unsigned*)(gp), (__attribute__((address_space(3))) unsigned*)(lp), 16, 0, 0)
; template <bool SWAP, class Epi, bool THIN = false> ...
;     ...
;     for (int st = 0; st < ns; ++st) {
;       asm volatile("s_waitcnt vmcnt(0)" ::: "memory");
;       __builtin_amdgcn_s_barrier();
;       asm volatile("" ::: "memory");
;       if (st + 1 < ns) {
;         char* nb = smem + ((st + 1) & 1) * 65536;
;         const int ko = (st + 1) * 64;
; #pragma unroll
;         for (int i = 0; i < 4; ++i) { GLDS16(A + (size_t)(ap[i] + ko), nb + tid * 16 + i * 8192); GLDS16(Bt + (size_t)(bp[i] + ko), nb + 32768 + tid * 16 + i * 8192); }
;       }
;       const char* sa = smem + (st & 1) * 65536 + (wr * 64 + fr) * 128;
;       const char* sb = smem + (st & 1) * 65536 + 32768 + (wc * 128 + fr) * 128;
;       if constexpr (THIN) {
;         if (wc == 0) {
; #pragma unroll
;           for (int ks = 0; ks < 2; ++ks) {
;             bf16x8 af[4], bf[2];
; #pragma unroll
;             for (int m = 0; m < 4; ++m) af[m] = *(const bf16x8*)(sa + m * 2048 + (((ks * 4 + fq) ^ swz) << 4));
; #pragma unroll
;             for (int n = 0; n < 2; ++n) bf[n] = *(const bf16x8*)(sb + n * 2048 + (((ks * 4 + fq) ^ swz) << 4));
; #pragma unroll
;             for (int m = 0; m < 4; ++m)
; #pragma unroll
;               for (int n = 0; n < 2; ++n)
;                 acc[m][n] = SWAP ? __builtin_amdgcn_mfma_f32_16x16x32_bf16(bf[n], af[m], acc[m][n], 0, 0, 0)
;                                  : __builtin_amdgcn_mfma_f32_16x16x32_bf16(af[m], bf[n], acc[m][n], 0, 0, 0);
;           }
;         }
.LBB0_1535:
	s_or_b64 exec, exec, s[6:7]
	s_waitcnt vmcnt(5)
	s_barrier
	v_readfirstlane_b32 s6, v56
	s_add_i32 m0, s6, 0x10000
	v_lshl_add_u64 v[4:5], v[46:47], 0, s[42:43]
	global_load_lds_dwordx4 v[4:5], off
	v_or_b32_e32 v2, 0x1c0, v38
	s_add_i32 m0, s6, 0x18000
	v_lshl_add_u64 v[4:5], v[2:3], 1, s[18:19]
	global_load_lds_dwordx4 v[4:5], off
	s_add_i32 m0, s6, 0x12000
	v_lshl_add_u64 v[4:5], v[48:49], 0, s[42:43]
	global_load_lds_dwordx4 v[4:5], off
	s_add_i32 m0, s6, 0x14000
	v_lshl_add_u64 v[4:5], v[50:51], 0, s[42:43]
	global_load_lds_dwordx4 v[4:5], off
	s_add_i32 m0, s6, 0x16000
	v_lshl_add_u64 v[4:5], v[52:53], 0, s[42:43]
	global_load_lds_dwordx4 v[4:5], off
	s_and_saveexec_b64 s[6:7], s[4:5]
	s_cbranch_execz .LBB0_1537
	ds_read_b128 v[94:97], v119 offset:32768
	ds_read_b128 v[98:101], v119 offset:34816
	ds_read_b128 v[102:105], v118
	ds_read_b128 v[106:109], v118 offset:2048
	ds_read_b128 v[122:125], v118 offset:4096
	ds_read_b128 v[126:129], v118 offset:6144
	ds_read_b128 v[130:133], v121 offset:32768
	ds_read_b128 v[134:137], v121 offset:34816
	ds_read_b128 v[138:141], v120
	ds_read_b128 v[142:145], v120 offset:2048
	ds_read_b128 v[146:149], v120 offset:4096
	ds_read_b128 v[150:153], v120 offset:6144
	s_waitcnt lgkmcnt(9)
	v_mfma_f32_16x16x32_bf16 v[34:37], v[94:97], v[102:105], v[34:37]
	v_mfma_f32_16x16x32_bf16 v[30:33], v[98:101], v[102:105], v[30:33]
	s_waitcnt lgkmcnt(8)
	v_mfma_f32_16x16x32_bf16 v[26:29], v[94:97], v[106:109], v[26:29]
	v_mfma_f32_16x16x32_bf16 v[22:25], v[98:101], v[106:109], v[22:25]
	s_waitcnt lgkmcnt(7)
	v_mfma_f32_16x16x32_bf16 v[18:21], v[94:97], v[122:125], v[18:21]
	v_mfma_f32_16x16x32_bf16 v[14:17], v[98:101], v[122:125], v[14:17]
	s_waitcnt lgkmcnt(6)
	v_mfma_f32_16x16x32_bf16 v[10:13], v[94:97], v[126:129], v[10:13]
	v_mfma_f32_16x16x32_bf16 v[6:9], v[98:101], v[126:129], v[6:9]
	s_waitcnt lgkmcnt(3)
	v_mfma_f32_16x16x32_bf16 v[34:37], v[130:133], v[138:141], v[34:37]
	v_mfma_f32_16x16x32_bf16 v[30:33], v[134:137], v[138:141], v[30:33]
	s_waitcnt lgkmcnt(2)
	v_mfma_f32_16x16x32_bf16 v[26:29], v[130:133], v[142:145], v[26:29]
	v_mfma_f32_16x16x32_bf16 v[22:25], v[134:137], v[142:145], v[22:25]
	s_waitcnt lgkmcnt(1)
	v_mfma_f32_16x16x32_bf16 v[18:21], v[130:133], v[146:149], v[18:21]
	v_mfma_f32_16x16x32_bf16 v[14:17], v[134:137], v[146:149], v[14:17]
	s_waitcnt lgkmcnt(0)
	v_mfma_f32_16x16x32_bf16 v[10:13], v[130:133], v[150:153], v[10:13]
	v_mfma_f32_16x16x32_bf16 v[6:9], v[134:137], v[150:153], v[6:9]
.LBB0_1537:
	s_or_b64 exec, exec, s[6:7]
	s_waitcnt vmcnt(5)
	s_barrier
	v_readfirstlane_b32 s6, v56
	s_add_i32 m0, s6, 0x1a000
	v_lshl_add_u64 v[4:5], v[46:47], 0, s[44:45]
	global_load_lds_dwordx4 v[4:5], off
	v_or_b32_e32 v2, 0x200, v38
	s_add_i32 m0, s6, 0x22000
	v_lshl_add_u64 v[4:5], v[2:3], 1, s[18:19]
	global_load_lds_dwordx4 v[4:5], off
	s_add_i32 m0, s6, 0x1c000
	v_lshl_add_u64 v[4:5], v[48:49], 0, s[44:45]
	global_load_lds_dwordx4 v[4:5], off
	s_add_i32 m0, s6, 0x1e000
	v_lshl_add_u64 v[4:5], v[50:51], 0, s[44:45]
	global_load_lds_dwordx4 v[4:5], off
	s_add_i32 m0, s6, 0x20000
	v_lshl_add_u64 v[4:5], v[52:53], 0, s[44:45]
	global_load_lds_dwordx4 v[4:5], off
	s_and_saveexec_b64 s[6:7], s[4:5]
	s_cbranch_execz .LBB0_1539
	ds_read_b128 v[94:97], v83 offset:32768
	ds_read_b128 v[98:101], v83 offset:34816
	ds_read_b128 v[102:105], v82
	ds_read_b128 v[106:109], v82 offset:2048
	ds_read_b128 v[122:125], v82 offset:4096
	ds_read_b128 v[126:129], v82 offset:6144
	ds_read_b128 v[130:133], v85 offset:32768
	ds_read_b128 v[134:137], v85 offset:34816
	ds_read_b128 v[138:141], v84
	ds_read_b128 v[142:145], v84 offset:2048
	ds_read_b128 v[146:149], v84 offset:4096
	ds_read_b128 v[150:153], v84 offset:6144
	s_waitcnt lgkmcnt(9)
	v_mfma_f32_16x16x32_bf16 v[34:37], v[94:97], v[102:105], v[34:37]
	v_mfma_f32_16x16x32_bf16 v[30:33], v[98:101], v[102:105], v[30:33]
	s_waitcnt lgkmcnt(8)
	v_mfma_f32_16x16x32_bf16 v[26:29], v[94:97], v[106:109], v[26:29]
	v_mfma_f32_16x16x32_bf16 v[22:25], v[98:101], v[106:109], v[22:25]
	s_waitcnt lgkmcnt(7)
	v_mfma_f32_16x16x32_bf16 v[18:21], v[94:97], v[122:125], v[18:21]
	v_mfma_f32_16x16x32_bf16 v[14:17], v[98:101], v[122:125], v[14:17]
	s_waitcnt lgkmcnt(6)
	v_mfma_f32_16x16x32_bf16 v[10:13], v[94:97], v[126:129], v[10:13]
	v_mfma_f32_16x16x32_bf16 v[6:9], v[98:101], v[126:129], v[6:9]
	s_waitcnt lgkmcnt(3)
	v_mfma_f32_16x16x32_bf16 v[34:37], v[130:133], v[138:141], v[34:37]
	v_mfma_f32_16x16x32_bf16 v[30:33], v[134:137], v[138:141], v[30:33]
	s_waitcnt lgkmcnt(2)
	v_mfma_f32_16x16x32_bf16 v[26:29], v[130:133], v[142:145], v[26:29]
	v_mfma_f32_16x16x32_bf16 v[22:25], v[134:137], v[142:145], v[22:25]
	s_waitcnt lgkmcnt(1)
	v_mfma_f32_16x16x32_bf16 v[18:21], v[130:133], v[146:149], v[18:21]
	v_mfma_f32_16x16x32_bf16 v[14:17], v[134:137], v[146:149], v[14:17]
	s_waitcnt lgkmcnt(0)
	v_mfma_f32_16x16x32_bf16 v[10:13], v[130:133], v[150:153], v[10:13]
	v_mfma_f32_16x16x32_bf16 v[6:9], v[134:137], v[150:153], v[6:9]
; #define GLDS16(gp, lp) __builtin_amdgcn_global_load_lds((const unsigned*)(gp), (__attribute__((address_space(3))) unsigned*)(lp), 16, 0, 0)
; template <bool SWAP, class Epi, bool THIN = false> ...
;     ...
;     for (int st = 0; st < ns; ++st) {
;       asm volatile("s_waitcnt vmcnt(0)" ::: "memory");
;       __builtin_amdgcn_s_barrier();
;       asm volatile("" ::: "memory");
;       if (st + 1 < ns) {
;         char* nb = smem + ((st + 1) & 1) * 65536;
;         const int ko = (st + 1) * 64;
; #pragma unroll
;         for (int i = 0; i < 4; ++i) { GLDS16(A + (size_t)(ap[i] + ko), nb + tid * 16 + i * 8192); GLDS16(Bt + (size_t)(bp[i] + ko), nb + 32768 + tid * 16 + i * 8192); }
;       }
;       const char* sa = smem + (st & 1) * 65536 + (wr * 64 + fr) * 128;
;       const char* sb = smem + (st & 1) * 65536 + 32768 + (wc * 128 + fr) * 128;
;       if constexpr (THIN) {
;         if (wc == 0) {
; #pragma unroll
;           for (int ks = 0; ks < 2; ++ks) {
;             bf16x8 af[4], bf[2];
; #pragma unroll
;             for (int m = 0; m < 4; ++m) af[m] = *(const bf16x8*)(sa + m * 2048 + (((ks * 4 + fq) ^ swz) << 4));
; #pragma unroll
;             for (int n = 0; n < 2; ++n) bf[n] = *(const bf16x8*)(sb + n * 2048 + (((ks * 4 + fq) ^ swz) << 4));
; #pragma unroll
;             for (int m = 0; m < 4; ++m)
; #pragma unroll
;               for (int n = 0; n < 2; ++n)
;                 acc[m][n] = SWAP ? __builtin_amdgcn_mfma_f32_16x16x32_bf16(bf[n], af[m], acc[m][n], 0, 0, 0)
;                                  : __builtin_amdgcn_mfma_f32_16x16x32_bf16(af[m], bf[n], acc[m][n], 0, 0, 0);
;           }
;         }
.LBB0_1539:
	s_or_b64 exec, exec, s[6:7]
	s_waitcnt vmcnt(5)
	s_barrier
	v_readfirstlane_b32 s6, v56
	s_add_i32 m0, s6, 0x0
	v_lshl_add_u64 v[4:5], v[46:47], 0, s[48:49]
	global_load_lds_dwordx4 v[4:5], off
	v_or_b32_e32 v2, 0x240, v38
	s_add_i32 m0, s6, 0x8000
	v_lshl_add_u64 v[4:5], v[2:3], 1, s[18:19]
	global_load_lds_dwordx4 v[4:5], off
	s_add_i32 m0, s6, 0x2000
	v_lshl_add_u64 v[4:5], v[48:49], 0, s[48:49]
	global_load_lds_dwordx4 v[4:5], off
	s_add_i32 m0, s6, 0x4000
	v_lshl_add_u64 v[4:5], v[50:51], 0, s[48:49]
	global_load_lds_dwordx4 v[4:5], off
	s_add_i32 m0, s6, 0x6000
	v_lshl_add_u64 v[4:5], v[52:53], 0, s[48:49]
	global_load_lds_dwordx4 v[4:5], off
	s_and_saveexec_b64 s[6:7], s[4:5]
	s_cbranch_execz .LBB0_1541
	ds_read_b128 v[94:97], v87
	ds_read_b128 v[98:101], v87 offset:2048
	ds_read_b128 v[102:105], v86
	ds_read_b128 v[106:109], v86 offset:2048
	ds_read_b128 v[122:125], v86 offset:4096
	ds_read_b128 v[126:129], v86 offset:6144
	ds_read_b128 v[130:133], v89
	ds_read_b128 v[134:137], v89 offset:2048
	ds_read_b128 v[138:141], v88
	ds_read_b128 v[142:145], v88 offset:2048
	ds_read_b128 v[146:149], v88 offset:4096
	ds_read_b128 v[150:153], v88 offset:6144
	s_waitcnt lgkmcnt(9)
	v_mfma_f32_16x16x32_bf16 v[34:37], v[94:97], v[102:105], v[34:37]
	v_mfma_f32_16x16x32_bf16 v[30:33], v[98:101], v[102:105], v[30:33]
	s_waitcnt lgkmcnt(8)
	v_mfma_f32_16x16x32_bf16 v[26:29], v[94:97], v[106:109], v[26:29]
	v_mfma_f32_16x16x32_bf16 v[22:25], v[98:101], v[106:109], v[22:25]
	s_waitcnt lgkmcnt(7)
	v_mfma_f32_16x16x32_bf16 v[18:21], v[94:97], v[122:125], v[18:21]
	v_mfma_f32_16x16x32_bf16 v[14:17], v[98:101], v[122:125], v[14:17]
	s_waitcnt lgkmcnt(6)
	v_mfma_f32_16x16x32_bf16 v[10:13], v[94:97], v[126:129], v[10:13]
	v_mfma_f32_16x16x32_bf16 v[6:9], v[98:101], v[126:129], v[6:9]
	s_waitcnt lgkmcnt(3)
	v_mfma_f32_16x16x32_bf16 v[34:37], v[130:133], v[138:141], v[34:37]
	v_mfma_f32_16x16x32_bf16 v[30:33], v[134:137], v[138:141], v[30:33]
	s_waitcnt lgkmcnt(2)
	v_mfma_f32_16x16x32_bf16 v[26:29], v[130:133], v[142:145], v[26:29]
	v_mfma_f32_16x16x32_bf16 v[22:25], v[134:137], v[142:145], v[22:25]
	s_waitcnt lgkmcnt(1)
	v_mfma_f32_16x16x32_bf16 v[18:21], v[130:133], v[146:149], v[18:21]
	v_mfma_f32_16x16x32_bf16 v[14:17], v[134:137], v[146:149], v[14:17]
	s_waitcnt lgkmcnt(0)
	v_mfma_f32_16x16x32_bf16 v[10:13], v[130:133], v[150:153], v[10:13]
	v_mfma_f32_16x16x32_bf16 v[6:9], v[134:137], v[150:153], v[6:9]
.LBB0_1541:
	s_or_b64 exec, exec, s[6:7]
	s_waitcnt vmcnt(5)
	s_barrier
	v_readfirstlane_b32 s6, v56
	s_add_i32 m0, s6, 0x10000
	v_lshl_add_u64 v[4:5], v[46:47], 0, s[50:51]
	global_load_lds_dwordx4 v[4:5], off
	v_or_b32_e32 v2, 0x280, v38
	s_add_i32 m0, s6, 0x18000
	v_lshl_add_u64 v[4:5], v[2:3], 1, s[18:19]
	global_load_lds_dwordx4 v[4:5], off
	s_add_i32 m0, s6, 0x12000
	v_lshl_add_u64 v[4:5], v[48:49], 0, s[50:51]
	global_load_lds_dwordx4 v[4:5], off
	s_add_i32 m0, s6, 0x14000
	v_lshl_add_u64 v[4:5], v[50:51], 0, s[50:51]
	global_load_lds_dwordx4 v[4:5], off
	s_add_i32 m0, s6, 0x16000
	v_lshl_add_u64 v[4:5], v[52:53], 0, s[50:51]
	global_load_lds_dwordx4 v[4:5], off
	s_and_saveexec_b64 s[6:7], s[4:5]
	s_cbranch_execz .LBB0_1543
	ds_read_b128 v[94:97], v119 offset:32768
	ds_read_b128 v[98:101], v119 offset:34816
	ds_read_b128 v[102:105], v118
	ds_read_b128 v[106:109], v118 offset:2048
	ds_read_b128 v[122:125], v118 offset:4096
	ds_read_b128 v[126:129], v118 offset:6144
	ds_read_b128 v[130:133], v121 offset:32768
	ds_read_b128 v[134:137], v121 offset:34816
	ds_read_b128 v[138:141], v120
	ds_read_b128 v[142:145], v120 offset:2048
	ds_read_b128 v[146:149], v120 offset:4096
	ds_read_b128 v[150:153], v120 offset:6144
	s_waitcnt lgkmcnt(9)
	v_mfma_f32_16x16x32_bf16 v[34:37], v[94:97], v[102:105], v[34:37]
	v_mfma_f32_16x16x32_bf16 v[30:33], v[98:101], v[102:105], v[30:33]
	s_waitcnt lgkmcnt(8)
	v_mfma_f32_16x16x32_bf16 v[26:29], v[94:97], v[106:109], v[26:29]
	v_mfma_f32_16x16x32_bf16 v[22:25], v[98:101], v[106:109], v[22:25]
	s_waitcnt lgkmcnt(7)
	v_mfma_f32_16x16x32_bf16 v[18:21], v[94:97], v[122:125], v[18:21]
	v_mfma_f32_16x16x32_bf16 v[14:17], v[98:101], v[122:125], v[14:17]
	s_waitcnt lgkmcnt(6)
	v_mfma_f32_16x16x32_bf16 v[10:13], v[94:97], v[126:129], v[10:13]
	v_mfma_f32_16x16x32_bf16 v[6:9], v[98:101], v[126:129], v[6:9]
	s_waitcnt lgkmcnt(3)
	v_mfma_f32_16x16x32_bf16 v[34:37], v[130:133], v[138:141], v[34:37]
	v_mfma_f32_16x16x32_bf16 v[30:33], v[134:137], v[138:141], v[30:33]
	s_waitcnt lgkmcnt(2)
	v_mfma_f32_16x16x32_bf16 v[26:29], v[130:133], v[142:145], v[26:29]
	v_mfma_f32_16x16x32_bf16 v[22:25], v[134:137], v[142:145], v[22:25]
	s_waitcnt lgkmcnt(1)
	v_mfma_f32_16x16x32_bf16 v[18:21], v[130:133], v[146:149], v[18:21]
	v_mfma_f32_16x16x32_bf16 v[14:17], v[134:137], v[146:149], v[14:17]
	s_waitcnt lgkmcnt(0)
	v_mfma_f32_16x16x32_bf16 v[10:13], v[130:133], v[150:153], v[10:13]
	v_mfma_f32_16x16x32_bf16 v[6:9], v[134:137], v[150:153], v[6:9]
; #define GLDS16(gp, lp) __builtin_amdgcn_global_load_lds((const unsigned*)(gp), (__attribute__((address_space(3))) unsigned*)(lp), 16, 0, 0)
; template <bool SWAP, class Epi, bool THIN = false> ...
;     ...
;     for (int st = 0; st < ns; ++st) {
;       asm volatile("s_waitcnt vmcnt(0)" ::: "memory");
;       __builtin_amdgcn_s_barrier();
;       asm volatile("" ::: "memory");
;       if (st + 1 < ns) {
;         char* nb = smem + ((st + 1) & 1) * 65536;
;         const int ko = (st + 1) * 64;
; #pragma unroll
;         for (int i = 0; i < 4; ++i) { GLDS16(A + (size_t)(ap[i] + ko), nb + tid * 16 + i * 8192); GLDS16(Bt + (size_t)(bp[i] + ko), nb + 32768 + tid * 16 + i * 8192); }
;       }
;       const char* sa = smem + (st & 1) * 65536 + (wr * 64 + fr) * 128;
;       const char* sb = smem + (st & 1) * 65536 + 32768 + (wc * 128 + fr) * 128;
;       if constexpr (THIN) {
;         if (wc == 0) {
; #pragma unroll
;           for (int ks = 0; ks < 2; ++ks) {
;             bf16x8 af[4], bf[2];
; #pragma unroll
;             for (int m = 0; m < 4; ++m) af[m] = *(const bf16x8*)(sa + m * 2048 + (((ks * 4 + fq) ^ swz) << 4));
; #pragma unroll
;             for (int n = 0; n < 2; ++n) bf[n] = *(const bf16x8*)(sb + n * 2048 + (((ks * 4 + fq) ^ swz) << 4));
; #pragma unroll
;             for (int m = 0; m < 4; ++m)
; #pragma unroll
;               for (int n = 0; n < 2; ++n)
;                 acc[m][n] = SWAP ? __builtin_amdgcn_mfma_f32_16x16x32_bf16(bf[n], af[m], acc[m][n], 0, 0, 0)
;                                  : __builtin_amdgcn_mfma_f32_16x16x32_bf16(af[m], bf[n], acc[m][n], 0, 0, 0);
;           }
;         }
.LBB0_1543:
	s_or_b64 exec, exec, s[6:7]
	s_waitcnt vmcnt(5)
	s_barrier
	v_readfirstlane_b32 s6, v56
	s_add_i32 m0, s6, 0x1a000
	v_lshl_add_u64 v[4:5], v[46:47], 0, s[56:57]
	global_load_lds_dwordx4 v[4:5], off
	v_or_b32_e32 v2, 0x2c0, v38
	s_add_i32 m0, s6, 0x22000
	v_lshl_add_u64 v[4:5], v[2:3], 1, s[18:19]
	global_load_lds_dwordx4 v[4:5], off
	s_add_i32 m0, s6, 0x1c000
	v_lshl_add_u64 v[4:5], v[48:49], 0, s[56:57]
	global_load_lds_dwordx4 v[4:5], off
	s_add_i32 m0, s6, 0x1e000
	v_lshl_add_u64 v[4:5], v[50:51], 0, s[56:57]
	global_load_lds_dwordx4 v[4:5], off
	s_add_i32 m0, s6, 0x20000
	v_lshl_add_u64 v[4:5], v[52:53], 0, s[56:57]
	global_load_lds_dwordx4 v[4:5], off
	s_and_saveexec_b64 s[6:7], s[4:5]
	s_cbranch_execz .LBB0_1545
	ds_read_b128 v[94:97], v83 offset:32768
	ds_read_b128 v[98:101], v83 offset:34816
	ds_read_b128 v[102:105], v82
	ds_read_b128 v[106:109], v82 offset:2048
	ds_read_b128 v[122:125], v82 offset:4096
	ds_read_b128 v[126:129], v82 offset:6144
	ds_read_b128 v[130:133], v85 offset:32768
	ds_read_b128 v[134:137], v85 offset:34816
	ds_read_b128 v[138:141], v84
	ds_read_b128 v[142:145], v84 offset:2048
	ds_read_b128 v[146:149], v84 offset:4096
	ds_read_b128 v[150:153], v84 offset:6144
	s_waitcnt lgkmcnt(9)
	v_mfma_f32_16x16x32_bf16 v[34:37], v[94:97], v[102:105], v[34:37]
	v_mfma_f32_16x16x32_bf16 v[30:33], v[98:101], v[102:105], v[30:33]
	s_waitcnt lgkmcnt(8)
	v_mfma_f32_16x16x32_bf16 v[26:29], v[94:97], v[106:109], v[26:29]
	v_mfma_f32_16x16x32_bf16 v[22:25], v[98:101], v[106:109], v[22:25]
	s_waitcnt lgkmcnt(7)
	v_mfma_f32_16x16x32_bf16 v[18:21], v[94:97], v[122:125], v[18:21]
	v_mfma_f32_16x16x32_bf16 v[14:17], v[98:101], v[122:125], v[14:17]
	s_waitcnt lgkmcnt(6)
	v_mfma_f32_16x16x32_bf16 v[10:13], v[94:97], v[126:129], v[10:13]
	v_mfma_f32_16x16x32_bf16 v[6:9], v[98:101], v[126:129], v[6:9]
	s_waitcnt lgkmcnt(3)
	v_mfma_f32_16x16x32_bf16 v[34:37], v[130:133], v[138:141], v[34:37]
	v_mfma_f32_16x16x32_bf16 v[30:33], v[134:137], v[138:141], v[30:33]
	s_waitcnt lgkmcnt(2)
	v_mfma_f32_16x16x32_bf16 v[26:29], v[130:133], v[142:145], v[26:29]
	v_mfma_f32_16x16x32_bf16 v[22:25], v[134:137], v[142:145], v[22:25]
	s_waitcnt lgkmcnt(1)
	v_mfma_f32_16x16x32_bf16 v[18:21], v[130:133], v[146:149], v[18:21]
	v_mfma_f32_16x16x32_bf16 v[14:17], v[134:137], v[146:149], v[14:17]
	s_waitcnt lgkmcnt(0)
	v_mfma_f32_16x16x32_bf16 v[10:13], v[130:133], v[150:153], v[10:13]
	v_mfma_f32_16x16x32_bf16 v[6:9], v[134:137], v[150:153], v[6:9]
.LBB0_1545:
	s_or_b64 exec, exec, s[6:7]
	s_waitcnt vmcnt(5)
	s_barrier
	v_readfirstlane_b32 s6, v56
	s_add_i32 m0, s6, 0x0
	v_lshl_add_u64 v[4:5], v[46:47], 0, s[58:59]
	global_load_lds_dwordx4 v[4:5], off
	v_or_b32_e32 v2, 0x300, v38
	s_add_i32 m0, s6, 0x8000
	v_lshl_add_u64 v[4:5], v[2:3], 1, s[18:19]
	global_load_lds_dwordx4 v[4:5], off
	s_add_i32 m0, s6, 0x2000
	v_lshl_add_u64 v[4:5], v[48:49], 0, s[58:59]
	global_load_lds_dwordx4 v[4:5], off
	s_add_i32 m0, s6, 0x4000
	v_lshl_add_u64 v[4:5], v[50:51], 0, s[58:59]
	global_load_lds_dwordx4 v[4:5], off
	s_add_i32 m0, s6, 0x6000
	v_lshl_add_u64 v[4:5], v[52:53], 0, s[58:59]
	global_load_lds_dwordx4 v[4:5], off
	s_and_saveexec_b64 s[6:7], s[4:5]
	s_cbranch_execz .LBB0_1547
	ds_read_b128 v[94:97], v87
	ds_read_b128 v[98:101], v87 offset:2048
	ds_read_b128 v[102:105], v86
	ds_read_b128 v[106:109], v86 offset:2048
	ds_read_b128 v[122:125], v86 offset:4096
	ds_read_b128 v[126:129], v86 offset:6144
	ds_read_b128 v[130:133], v89
	ds_read_b128 v[134:137], v89 offset:2048
	ds_read_b128 v[138:141], v88
	ds_read_b128 v[142:145], v88 offset:2048
	ds_read_b128 v[146:149], v88 offset:4096
	ds_read_b128 v[150:153], v88 offset:6144
	s_waitcnt lgkmcnt(9)
	v_mfma_f32_16x16x32_bf16 v[34:37], v[94:97], v[102:105], v[34:37]
	v_mfma_f32_16x16x32_bf16 v[30:33], v[98:101], v[102:105], v[30:33]
	s_waitcnt lgkmcnt(8)
	v_mfma_f32_16x16x32_bf16 v[26:29], v[94:97], v[106:109], v[26:29]
	v_mfma_f32_16x16x32_bf16 v[22:25], v[98:101], v[106:109], v[22:25]
	s_waitcnt lgkmcnt(7)
	v_mfma_f32_16x16x32_bf16 v[18:21], v[94:97], v[122:125], v[18:21]
	v_mfma_f32_16x16x32_bf16 v[14:17], v[98:101], v[122:125], v[14:17]
	s_waitcnt lgkmcnt(6)
	v_mfma_f32_16x16x32_bf16 v[10:13], v[94:97], v[126:129], v[10:13]
	v_mfma_f32_16x16x32_bf16 v[6:9], v[98:101], v[126:129], v[6:9]
	s_waitcnt lgkmcnt(3)
	v_mfma_f32_16x16x32_bf16 v[34:37], v[130:133], v[138:141], v[34:37]
	v_mfma_f32_16x16x32_bf16 v[30:33], v[134:137], v[138:141], v[30:33]
	s_waitcnt lgkmcnt(2)
	v_mfma_f32_16x16x32_bf16 v[26:29], v[130:133], v[142:145], v[26:29]
	v_mfma_f32_16x16x32_bf16 v[22:25], v[134:137], v[142:145], v[22:25]
	s_waitcnt lgkmcnt(1)
	v_mfma_f32_16x16x32_bf16 v[18:21], v[130:133], v[146:149], v[18:21]
	v_mfma_f32_16x16x32_bf16 v[14:17], v[134:137], v[146:149], v[14:17]
	s_waitcnt lgkmcnt(0)
	v_mfma_f32_16x16x32_bf16 v[10:13], v[130:133], v[150:153], v[10:13]
	v_mfma_f32_16x16x32_bf16 v[6:9], v[134:137], v[150:153], v[6:9]
; #define GLDS16(gp, lp) __builtin_amdgcn_global_load_lds((const unsigned*)(gp), (__attribute__((address_space(3))) unsigned*)(lp), 16, 0, 0)
; template <bool SWAP, class Epi, bool THIN = false> ...
;     ...
;     for (int st = 0; st < ns; ++st) {
;       asm volatile("s_waitcnt vmcnt(0)" ::: "memory");
;       __builtin_amdgcn_s_barrier();
;       asm volatile("" ::: "memory");
;       if (st + 1 < ns) {
;         char* nb = smem + ((st + 1) & 1) * 65536;
;         const int ko = (st + 1) * 64;
; #pragma unroll
;         for (int i = 0; i < 4; ++i) { GLDS16(A + (size_t)(ap[i] + ko), nb + tid * 16 + i * 8192); GLDS16(Bt + (size_t)(bp[i] + ko), nb + 32768 + tid * 16 + i * 8192); }
;       }
;       const char* sa = smem + (st & 1) * 65536 + (wr * 64 + fr) * 128;
;       const char* sb = smem + (st & 1) * 65536 + 32768 + (wc * 128 + fr) * 128;
;       if constexpr (THIN) {
;         if (wc == 0) {
; #pragma unroll
;           for (int ks = 0; ks < 2; ++ks) {
;             bf16x8 af[4], bf[2];
; #pragma unroll
;             for (int m = 0; m < 4; ++m) af[m] = *(const bf16x8*)(sa + m * 2048 + (((ks * 4 + fq) ^ swz) << 4));
; #pragma unroll
;             for (int n = 0; n < 2; ++n) bf[n] = *(const bf16x8*)(sb + n * 2048 + (((ks * 4 + fq) ^ swz) << 4));
; #pragma unroll
;             for (int m = 0; m < 4; ++m)
; #pragma unroll
;               for (int n = 0; n < 2; ++n)
;                 acc[m][n] = SWAP ? __builtin_amdgcn_mfma_f32_16x16x32_bf16(bf[n], af[m], acc[m][n], 0, 0, 0)
;                                  : __builtin_amdgcn_mfma_f32_16x16x32_bf16(af[m], bf[n], acc[m][n], 0, 0, 0);
;           }
;         }
.LBB0_1547:
	s_or_b64 exec, exec, s[6:7]
	s_waitcnt vmcnt(5)
	s_barrier
	v_readfirstlane_b32 s6, v56
	s_add_i32 m0, s6, 0x10000
	v_lshl_add_u64 v[4:5], v[46:47], 0, s[60:61]
	global_load_lds_dwordx4 v[4:5], off
	v_or_b32_e32 v2, 0x340, v38
	s_add_i32 m0, s6, 0x18000
	v_lshl_add_u64 v[4:5], v[2:3], 1, s[18:19]
	global_load_lds_dwordx4 v[4:5], off
	s_add_i32 m0, s6, 0x12000
	v_lshl_add_u64 v[4:5], v[48:49], 0, s[60:61]
	global_load_lds_dwordx4 v[4:5], off
	s_add_i32 m0, s6, 0x14000
	v_lshl_add_u64 v[4:5], v[50:51], 0, s[60:61]
	global_load_lds_dwordx4 v[4:5], off
	s_add_i32 m0, s6, 0x16000
	v_lshl_add_u64 v[4:5], v[52:53], 0, s[60:61]
	global_load_lds_dwordx4 v[4:5], off
	s_and_saveexec_b64 s[6:7], s[4:5]
	s_cbranch_execz .LBB0_1549
	ds_read_b128 v[94:97], v119 offset:32768
	ds_read_b128 v[98:101], v119 offset:34816
	ds_read_b128 v[102:105], v118
	ds_read_b128 v[106:109], v118 offset:2048
	ds_read_b128 v[122:125], v118 offset:4096
	ds_read_b128 v[126:129], v118 offset:6144
	ds_read_b128 v[130:133], v121 offset:32768
	ds_read_b128 v[134:137], v121 offset:34816
	ds_read_b128 v[138:141], v120
	ds_read_b128 v[142:145], v120 offset:2048
	ds_read_b128 v[146:149], v120 offset:4096
	ds_read_b128 v[150:153], v120 offset:6144
	s_waitcnt lgkmcnt(9)
	v_mfma_f32_16x16x32_bf16 v[34:37], v[94:97], v[102:105], v[34:37]
	v_mfma_f32_16x16x32_bf16 v[30:33], v[98:101], v[102:105], v[30:33]
	s_waitcnt lgkmcnt(8)
	v_mfma_f32_16x16x32_bf16 v[26:29], v[94:97], v[106:109], v[26:29]
	v_mfma_f32_16x16x32_bf16 v[22:25], v[98:101], v[106:109], v[22:25]
	s_waitcnt lgkmcnt(7)
	v_mfma_f32_16x16x32_bf16 v[18:21], v[94:97], v[122:125], v[18:21]
	v_mfma_f32_16x16x32_bf16 v[14:17], v[98:101], v[122:125], v[14:17]
	s_waitcnt lgkmcnt(6)
	v_mfma_f32_16x16x32_bf16 v[10:13], v[94:97], v[126:129], v[10:13]
	v_mfma_f32_16x16x32_bf16 v[6:9], v[98:101], v[126:129], v[6:9]
	s_waitcnt lgkmcnt(3)
	v_mfma_f32_16x16x32_bf16 v[34:37], v[130:133], v[138:141], v[34:37]
	v_mfma_f32_16x16x32_bf16 v[30:33], v[134:137], v[138:141], v[30:33]
	s_waitcnt lgkmcnt(2)
	v_mfma_f32_16x16x32_bf16 v[26:29], v[130:133], v[142:145], v[26:29]
	v_mfma_f32_16x16x32_bf16 v[22:25], v[134:137], v[142:145], v[22:25]
	s_waitcnt lgkmcnt(1)
	v_mfma_f32_16x16x32_bf16 v[18:21], v[130:133], v[146:149], v[18:21]
	v_mfma_f32_16x16x32_bf16 v[14:17], v[134:137], v[146:149], v[14:17]
	s_waitcnt lgkmcnt(0)
	v_mfma_f32_16x16x32_bf16 v[10:13], v[130:133], v[150:153], v[10:13]
	v_mfma_f32_16x16x32_bf16 v[6:9], v[134:137], v[150:153], v[6:9]
.LBB0_1549:
	s_or_b64 exec, exec, s[6:7]
	s_waitcnt vmcnt(5)
	s_barrier
	v_readfirstlane_b32 s6, v56
	s_add_i32 m0, s6, 0x1a000
	v_lshl_add_u64 v[4:5], v[46:47], 0, s[62:63]
	global_load_lds_dwordx4 v[4:5], off
	v_or_b32_e32 v2, 0x380, v38
	s_add_i32 m0, s6, 0x22000
	v_lshl_add_u64 v[4:5], v[2:3], 1, s[18:19]
	global_load_lds_dwordx4 v[4:5], off
	s_add_i32 m0, s6, 0x1c000
	v_lshl_add_u64 v[4:5], v[48:49], 0, s[62:63]
	global_load_lds_dwordx4 v[4:5], off
	s_add_i32 m0, s6, 0x1e000
	v_lshl_add_u64 v[4:5], v[50:51], 0, s[62:63]
	global_load_lds_dwordx4 v[4:5], off
	s_add_i32 m0, s6, 0x20000
	v_lshl_add_u64 v[4:5], v[52:53], 0, s[62:63]
	global_load_lds_dwordx4 v[4:5], off
	s_and_saveexec_b64 s[6:7], s[4:5]
	s_cbranch_execz .LBB0_1551
	ds_read_b128 v[94:97], v83 offset:32768
	ds_read_b128 v[98:101], v83 offset:34816
	ds_read_b128 v[102:105], v82
	ds_read_b128 v[106:109], v82 offset:2048
	ds_read_b128 v[122:125], v82 offset:4096
	ds_read_b128 v[126:129], v82 offset:6144
	ds_read_b128 v[130:133], v85 offset:32768
	ds_read_b128 v[134:137], v85 offset:34816
	ds_read_b128 v[138:141], v84
	ds_read_b128 v[142:145], v84 offset:2048
	ds_read_b128 v[146:149], v84 offset:4096
	ds_read_b128 v[150:153], v84 offset:6144
	s_waitcnt lgkmcnt(9)
	v_mfma_f32_16x16x32_bf16 v[34:37], v[94:97], v[102:105], v[34:37]
	v_mfma_f32_16x16x32_bf16 v[30:33], v[98:101], v[102:105], v[30:33]
	s_waitcnt lgkmcnt(8)
	v_mfma_f32_16x16x32_bf16 v[26:29], v[94:97], v[106:109], v[26:29]
	v_mfma_f32_16x16x32_bf16 v[22:25], v[98:101], v[106:109], v[22:25]
	s_waitcnt lgkmcnt(7)
	v_mfma_f32_16x16x32_bf16 v[18:21], v[94:97], v[122:125], v[18:21]
	v_mfma_f32_16x16x32_bf16 v[14:17], v[98:101], v[122:125], v[14:17]
	s_waitcnt lgkmcnt(6)
	v_mfma_f32_16x16x32_bf16 v[10:13], v[94:97], v[126:129], v[10:13]
	v_mfma_f32_16x16x32_bf16 v[6:9], v[98:101], v[126:129], v[6:9]
	s_waitcnt lgkmcnt(3)
	v_mfma_f32_16x16x32_bf16 v[34:37], v[130:133], v[138:141], v[34:37]
	v_mfma_f32_16x16x32_bf16 v[30:33], v[134:137], v[138:141], v[30:33]
	s_waitcnt lgkmcnt(2)
	v_mfma_f32_16x16x32_bf16 v[26:29], v[130:133], v[142:145], v[26:29]
	v_mfma_f32_16x16x32_bf16 v[22:25], v[134:137], v[142:145], v[22:25]
	s_waitcnt lgkmcnt(1)
	v_mfma_f32_16x16x32_bf16 v[18:21], v[130:133], v[146:149], v[18:21]
	v_mfma_f32_16x16x32_bf16 v[14:17], v[134:137], v[146:149], v[14:17]
	s_waitcnt lgkmcnt(0)
	v_mfma_f32_16x16x32_bf16 v[10:13], v[130:133], v[150:153], v[10:13]
	v_mfma_f32_16x16x32_bf16 v[6:9], v[134:137], v[150:153], v[6:9]
; #define GLDS16(gp, lp) __builtin_amdgcn_global_load_lds((const unsigned*)(gp), (__attribute__((address_space(3))) unsigned*)(lp), 16, 0, 0)
; template <bool SWAP, class Epi, bool THIN = false> ...
;     ...
;     for (int st = 0; st < ns; ++st) {
;       asm volatile("s_waitcnt vmcnt(0)" ::: "memory");
;       __builtin_amdgcn_s_barrier();
;       asm volatile("" ::: "memory");
;       if (st + 1 < ns) {
;         char* nb = smem + ((st + 1) & 1) * 65536;
;         const int ko = (st + 1) * 64;
; #pragma unroll
;         for (int i = 0; i < 4; ++i) { GLDS16(A + (size_t)(ap[i] + ko), nb + tid * 16 + i * 8192); GLDS16(Bt + (size_t)(bp[i] + ko), nb + 32768 + tid * 16 + i * 8192); }
;       }
;       const char* sa = smem + (st & 1) * 65536 + (wr * 64 + fr) * 128;
;       const char* sb = smem + (st & 1) * 65536 + 32768 + (wc * 128 + fr) * 128;
;       if constexpr (THIN) {
;         if (wc == 0) {
; #pragma unroll
;           for (int ks = 0; ks < 2; ++ks) {
;             bf16x8 af[4], bf[2];
; #pragma unroll
;             for (int m = 0; m < 4; ++m) af[m] = *(const bf16x8*)(sa + m * 2048 + (((ks * 4 + fq) ^ swz) << 4));
; #pragma unroll
;             for (int n = 0; n < 2; ++n) bf[n] = *(const bf16x8*)(sb + n * 2048 + (((ks * 4 + fq) ^ swz) << 4));
; #pragma unroll
;             for (int m = 0; m < 4; ++m)
; #pragma unroll
;               for (int n = 0; n < 2; ++n)
;                 acc[m][n] = SWAP ? __builtin_amdgcn_mfma_f32_16x16x32_bf16(bf[n], af[m], acc[m][n], 0, 0, 0)
;                                  : __builtin_amdgcn_mfma_f32_16x16x32_bf16(af[m], bf[n], acc[m][n], 0, 0, 0);
;           }
;         }
.LBB0_1551:
	s_or_b64 exec, exec, s[6:7]
	s_waitcnt vmcnt(5)
	s_barrier
	v_readfirstlane_b32 s6, v56
	s_add_i32 m0, s6, 0x0
	v_lshl_add_u64 v[4:5], v[46:47], 0, s[64:65]
	global_load_lds_dwordx4 v[4:5], off
	v_or_b32_e32 v2, 0x3c0, v38
	s_add_i32 m0, s6, 0x8000
	v_lshl_add_u64 v[4:5], v[2:3], 1, s[18:19]
	global_load_lds_dwordx4 v[4:5], off
	s_add_i32 m0, s6, 0x2000
	v_lshl_add_u64 v[4:5], v[48:49], 0, s[64:65]
	global_load_lds_dwordx4 v[4:5], off
	s_add_i32 m0, s6, 0x4000
	v_lshl_add_u64 v[4:5], v[50:51], 0, s[64:65]
	global_load_lds_dwordx4 v[4:5], off
	s_add_i32 m0, s6, 0x6000
	v_lshl_add_u64 v[4:5], v[52:53], 0, s[64:65]
	global_load_lds_dwordx4 v[4:5], off
	s_and_saveexec_b64 s[6:7], s[4:5]
	s_cbranch_execz .LBB0_1553
	ds_read_b128 v[94:97], v87
	ds_read_b128 v[98:101], v87 offset:2048
	ds_read_b128 v[102:105], v86
	ds_read_b128 v[106:109], v86 offset:2048
	ds_read_b128 v[122:125], v86 offset:4096
	ds_read_b128 v[126:129], v86 offset:6144
	ds_read_b128 v[130:133], v89
	ds_read_b128 v[134:137], v89 offset:2048
	ds_read_b128 v[138:141], v88
	ds_read_b128 v[142:145], v88 offset:2048
	ds_read_b128 v[146:149], v88 offset:4096
	ds_read_b128 v[150:153], v88 offset:6144
	s_waitcnt lgkmcnt(9)
	v_mfma_f32_16x16x32_bf16 v[34:37], v[94:97], v[102:105], v[34:37]
	v_mfma_f32_16x16x32_bf16 v[30:33], v[98:101], v[102:105], v[30:33]
	s_waitcnt lgkmcnt(8)
	v_mfma_f32_16x16x32_bf16 v[26:29], v[94:97], v[106:109], v[26:29]
	v_mfma_f32_16x16x32_bf16 v[22:25], v[98:101], v[106:109], v[22:25]
	s_waitcnt lgkmcnt(7)
	v_mfma_f32_16x16x32_bf16 v[18:21], v[94:97], v[122:125], v[18:21]
	v_mfma_f32_16x16x32_bf16 v[14:17], v[98:101], v[122:125], v[14:17]
	s_waitcnt lgkmcnt(6)
	v_mfma_f32_16x16x32_bf16 v[10:13], v[94:97], v[126:129], v[10:13]
	v_mfma_f32_16x16x32_bf16 v[6:9], v[98:101], v[126:129], v[6:9]
	s_waitcnt lgkmcnt(3)
	v_mfma_f32_16x16x32_bf16 v[34:37], v[130:133], v[138:141], v[34:37]
	v_mfma_f32_16x16x32_bf16 v[30:33], v[134:137], v[138:141], v[30:33]
	s_waitcnt lgkmcnt(2)
	v_mfma_f32_16x16x32_bf16 v[26:29], v[130:133], v[142:145], v[26:29]
	v_mfma_f32_16x16x32_bf16 v[22:25], v[134:137], v[142:145], v[22:25]
	s_waitcnt lgkmcnt(1)
	v_mfma_f32_16x16x32_bf16 v[18:21], v[130:133], v[146:149], v[18:21]
	v_mfma_f32_16x16x32_bf16 v[14:17], v[134:137], v[146:149], v[14:17]
	s_waitcnt lgkmcnt(0)
	v_mfma_f32_16x16x32_bf16 v[10:13], v[130:133], v[150:153], v[10:13]
	v_mfma_f32_16x16x32_bf16 v[6:9], v[134:137], v[150:153], v[6:9]
.LBB0_1553:
	s_or_b64 exec, exec, s[6:7]
	s_waitcnt vmcnt(5)
	s_barrier
	s_and_saveexec_b64 s[6:7], s[4:5]
	s_cbranch_execz .LBB0_1555
	ds_read_b128 v[94:97], v119 offset:32768
	ds_read_b128 v[98:101], v119 offset:34816
	ds_read_b128 v[102:105], v118
	ds_read_b128 v[106:109], v118 offset:2048
	ds_read_b128 v[122:125], v118 offset:4096
	ds_read_b128 v[126:129], v118 offset:6144
	ds_read_b128 v[130:133], v121 offset:32768
	ds_read_b128 v[134:137], v121 offset:34816
	ds_read_b128 v[138:141], v120
	ds_read_b128 v[142:145], v120 offset:2048
	ds_read_b128 v[146:149], v120 offset:4096
	ds_read_b128 v[150:153], v120 offset:6144
	s_waitcnt lgkmcnt(9)
	v_mfma_f32_16x16x32_bf16 v[34:37], v[94:97], v[102:105], v[34:37]
	v_mfma_f32_16x16x32_bf16 v[30:33], v[98:101], v[102:105], v[30:33]
	s_waitcnt lgkmcnt(8)
	v_mfma_f32_16x16x32_bf16 v[26:29], v[94:97], v[106:109], v[26:29]
	v_mfma_f32_16x16x32_bf16 v[22:25], v[98:101], v[106:109], v[22:25]
	s_waitcnt lgkmcnt(7)
	v_mfma_f32_16x16x32_bf16 v[18:21], v[94:97], v[122:125], v[18:21]
	v_mfma_f32_16x16x32_bf16 v[14:17], v[98:101], v[122:125], v[14:17]
	s_waitcnt lgkmcnt(6)
	v_mfma_f32_16x16x32_bf16 v[10:13], v[94:97], v[126:129], v[10:13]
	v_mfma_f32_16x16x32_bf16 v[6:9], v[98:101], v[126:129], v[6:9]
	s_waitcnt lgkmcnt(3)
	v_mfma_f32_16x16x32_bf16 v[34:37], v[130:133], v[138:141], v[34:37]
	v_mfma_f32_16x16x32_bf16 v[30:33], v[134:137], v[138:141], v[30:33]
	s_waitcnt lgkmcnt(2)
	v_mfma_f32_16x16x32_bf16 v[26:29], v[130:133], v[142:145], v[26:29]
	v_mfma_f32_16x16x32_bf16 v[22:25], v[134:137], v[142:145], v[22:25]
	s_waitcnt lgkmcnt(1)
	v_mfma_f32_16x16x32_bf16 v[18:21], v[130:133], v[146:149], v[18:21]
	v_mfma_f32_16x16x32_bf16 v[14:17], v[134:137], v[146:149], v[14:17]
	s_waitcnt lgkmcnt(0)
	v_mfma_f32_16x16x32_bf16 v[10:13], v[130:133], v[150:153], v[10:13]
	v_mfma_f32_16x16x32_bf16 v[6:9], v[134:137], v[150:153], v[6:9]
.LBB0_1555:
	s_or_b64 exec, exec, s[6:7]
	s_waitcnt vmcnt(0)
	s_barrier
	s_and_saveexec_b64 s[6:7], s[4:5]
	s_xor_b64 s[6:7], exec, s[6:7]
	s_cbranch_execz .LBB0_1557
	ds_read_b128 v[94:97], v83 offset:32768
	ds_read_b128 v[98:101], v83 offset:34816
	ds_read_b128 v[102:105], v82
	ds_read_b128 v[106:109], v82 offset:2048
	ds_read_b128 v[122:125], v82 offset:4096
	ds_read_b128 v[126:129], v82 offset:6144
	ds_read_b128 v[130:133], v85 offset:32768
	ds_read_b128 v[134:137], v85 offset:34816
	ds_read_b128 v[138:141], v84
	ds_read_b128 v[142:145], v84 offset:2048
	ds_read_b128 v[146:149], v84 offset:4096
	ds_read_b128 v[150:153], v84 offset:6144
	s_waitcnt lgkmcnt(9)
	v_mfma_f32_16x16x32_bf16 v[34:37], v[94:97], v[102:105], v[34:37]
	v_mfma_f32_16x16x32_bf16 v[30:33], v[98:101], v[102:105], v[30:33]
	s_waitcnt lgkmcnt(8)
	v_mfma_f32_16x16x32_bf16 v[26:29], v[94:97], v[106:109], v[26:29]
	v_mfma_f32_16x16x32_bf16 v[22:25], v[98:101], v[106:109], v[22:25]
	s_waitcnt lgkmcnt(7)
	v_mfma_f32_16x16x32_bf16 v[18:21], v[94:97], v[122:125], v[18:21]
	v_mfma_f32_16x16x32_bf16 v[14:17], v[98:101], v[122:125], v[14:17]
	s_waitcnt lgkmcnt(6)
	v_mfma_f32_16x16x32_bf16 v[10:13], v[94:97], v[126:129], v[10:13]
	v_mfma_f32_16x16x32_bf16 v[6:9], v[98:101], v[126:129], v[6:9]
	s_waitcnt lgkmcnt(3)
	v_mfma_f32_16x16x32_bf16 v[34:37], v[130:133], v[138:141], v[34:37]
	v_mfma_f32_16x16x32_bf16 v[30:33], v[134:137], v[138:141], v[30:33]
	s_waitcnt lgkmcnt(2)
	v_mfma_f32_16x16x32_bf16 v[26:29], v[130:133], v[142:145], v[26:29]
	v_mfma_f32_16x16x32_bf16 v[22:25], v[134:137], v[142:145], v[22:25]
	s_waitcnt lgkmcnt(1)
	v_mfma_f32_16x16x32_bf16 v[18:21], v[130:133], v[146:149], v[18:21]
	v_mfma_f32_16x16x32_bf16 v[14:17], v[134:137], v[146:149], v[14:17]
	s_waitcnt lgkmcnt(0)
	v_mfma_f32_16x16x32_bf16 v[10:13], v[130:133], v[150:153], v[10:13]
	v_mfma_f32_16x16x32_bf16 v[6:9], v[134:137], v[150:153], v[6:9]
